# v76 + selective cache policy in P3 epilogue: the sigmoid-gate tiles of Z (consumed only in P7's epilogue) stored nt, mixer-input tiles default
# speedup vs baseline: 1.0049x; 1.0049x over previous
; __device__ __forceinline__ unsigned pk2(float lo, float hi) { unsigned r; asm("v_cvt_pk_bf16_f32 %0, %1, %2" : "=v"(r) : "v"(lo), "v"(hi)); return r; }
; __device__ __forceinline__ float sigmoidf_(float x) { return __builtin_amdgcn_rcpf(1.0f + __expf(-x)); }
;     __device__ __forceinline__ void operator()(const f32x4 (&acc)[2][2][4][2], const Unit& u, int wr, int wc, int fr, int fq) const {
;     ...
;             for (int m = 0; m < 4; ++m) { bf16_t* rowp = O + (size_t)(row0 + ai * HALF + m * 16) * ldc + col0;
; #pragma unroll
;                 for (int bj = 0; bj < 2; ++bj) { f32x4 v0 = acc[ai][bj][m][0], v1 = acc[ai][bj][m][1];
;                     if (sg) {
; #pragma unroll
;                         for (int j = 0; j < 4; ++j) { v0[j] = sigmoidf_(v0[j]); v1[j] = sigmoidf_(v1[j]); } }
;                     u32x4 w; w.x = pk2(v0[0], v0[1]); w.y = pk2(v0[2], v0[3]); w.z = pk2(v1[0], v1[1]); w.w = pk2(v1[2], v1[3]);
;                     *(u32x4*)(rowp + bj * HALF) = w; } }
.LBB0_239:
	v_lshl_add_u32 v152, s6, 8, v146
	v_lshl_or_b32 v142, s78, 8, v148
	v_mov_b64_e32 v[144:145], s[40:41]
	v_ashrrev_i32_e32 v143, 31, v142
	v_mad_i64_i32 v[144:145], s[6:7], v152, s75, v[144:145]
	v_cvt_pk_bf16_f32 v124, v124, v125
	v_cvt_pk_bf16_f32 v125, v126, v127
	v_cvt_pk_bf16_f32 v126, v120, v121
	v_cndmask_b32_e64 v120, 0, 1, s[0:1]
	v_lshl_add_u64 v[144:145], v[142:143], 1, v[144:145]
	v_cmp_ne_u32_e64 s[6:7], 1, v120
	s_andn2_b64 vcc, exec, s[0:1]
	v_cvt_pk_bf16_f32 v127, v122, v123
	s_cbranch_vccnz .Lzsel_p0
	global_store_dwordx4 v[144:145], v[124:127], off nt
	s_branch .Lzsel_s0
.Lzsel_p0:
	global_store_dwordx4 v[144:145], v[124:127], off
	s_branch .LBB0_241
.Lzsel_s0:
	v_mul_f32_e32 v116, 0xbfb8aa3b, v116
	v_mul_f32_e32 v112, 0xbfb8aa3b, v112
	v_mul_f32_e32 v117, 0xbfb8aa3b, v117
	v_mul_f32_e32 v113, 0xbfb8aa3b, v113
	v_mul_f32_e32 v118, 0xbfb8aa3b, v118
	v_mul_f32_e32 v114, 0xbfb8aa3b, v114
	v_mul_f32_e32 v119, 0xbfb8aa3b, v119
	v_mul_f32_e32 v115, 0xbfb8aa3b, v115
	v_exp_f32_e32 v116, v116
	v_exp_f32_e32 v112, v112
	v_exp_f32_e32 v117, v117
	v_exp_f32_e32 v113, v113
	v_exp_f32_e32 v118, v118
	v_exp_f32_e32 v114, v114
	v_exp_f32_e32 v119, v119
	v_exp_f32_e32 v115, v115
	v_add_f32_e32 v116, 1.0, v116
	v_add_f32_e32 v112, 1.0, v112
	v_add_f32_e32 v117, 1.0, v117
	v_add_f32_e32 v113, 1.0, v113
	v_add_f32_e32 v118, 1.0, v118
	v_add_f32_e32 v114, 1.0, v114
	v_add_f32_e32 v119, 1.0, v119
	v_add_f32_e32 v115, 1.0, v115
	v_rcp_f32_e32 v116, v116
	v_rcp_f32_e32 v112, v112
	v_rcp_f32_e32 v117, v117
	v_rcp_f32_e32 v113, v113
	v_rcp_f32_e32 v118, v118
	v_rcp_f32_e32 v114, v114
	v_rcp_f32_e32 v119, v119
	v_rcp_f32_e32 v115, v115
.LBB0_241:
	s_and_b64 vcc, exec, s[6:7]
	v_cvt_pk_bf16_f32 v116, v116, v117
	v_cvt_pk_bf16_f32 v117, v118, v119
	v_cvt_pk_bf16_f32 v118, v112, v113
	v_cvt_pk_bf16_f32 v119, v114, v115
	s_cbranch_vccnz .Lzsel_p1
	global_store_dwordx4 v[144:145], v[116:119], off offset:256 nt
	s_branch .Lzsel_s1
.Lzsel_p1:
	global_store_dwordx4 v[144:145], v[116:119], off offset:256
	s_branch .LBB0_243
.Lzsel_s1:
	v_mul_f32_e32 v108, 0xbfb8aa3b, v108
	v_mul_f32_e32 v104, 0xbfb8aa3b, v104
	v_mul_f32_e32 v109, 0xbfb8aa3b, v109
	v_mul_f32_e32 v105, 0xbfb8aa3b, v105
	v_mul_f32_e32 v110, 0xbfb8aa3b, v110
	v_mul_f32_e32 v106, 0xbfb8aa3b, v106
	v_mul_f32_e32 v111, 0xbfb8aa3b, v111
	v_mul_f32_e32 v107, 0xbfb8aa3b, v107
	v_exp_f32_e32 v108, v108
	v_exp_f32_e32 v104, v104
	v_exp_f32_e32 v109, v109
	v_exp_f32_e32 v105, v105
	v_exp_f32_e32 v110, v110
	v_exp_f32_e32 v106, v106
	v_exp_f32_e32 v111, v111
	v_exp_f32_e32 v107, v107
	v_add_f32_e32 v108, 1.0, v108
	v_add_f32_e32 v104, 1.0, v104
	v_add_f32_e32 v109, 1.0, v109
	v_add_f32_e32 v105, 1.0, v105
	v_add_f32_e32 v110, 1.0, v110
	v_add_f32_e32 v106, 1.0, v106
	v_add_f32_e32 v111, 1.0, v111
	v_add_f32_e32 v107, 1.0, v107
	v_rcp_f32_e32 v108, v108
	v_rcp_f32_e32 v104, v104
	v_rcp_f32_e32 v109, v109
	v_rcp_f32_e32 v105, v105
	v_rcp_f32_e32 v110, v110
	v_rcp_f32_e32 v106, v106
	v_rcp_f32_e32 v111, v111
	v_rcp_f32_e32 v107, v107
.LBB0_243:
	v_or_b32_e32 v114, 16, v152
	v_mov_b64_e32 v[112:113], s[40:41]
	v_mad_i64_i32 v[112:113], s[0:1], v114, s75, v[112:113]
	v_lshl_add_u64 v[112:113], v[142:143], 1, v[112:113]
	s_and_b64 vcc, exec, s[6:7]
	v_cvt_pk_bf16_f32 v108, v108, v109
	v_cvt_pk_bf16_f32 v109, v110, v111
	v_cvt_pk_bf16_f32 v110, v104, v105
	v_cvt_pk_bf16_f32 v111, v106, v107
	s_cbranch_vccnz .Lzsel_p2
	global_store_dwordx4 v[112:113], v[108:111], off nt
	s_branch .Lzsel_s2
.Lzsel_p2:
	global_store_dwordx4 v[112:113], v[108:111], off
	s_branch .LBB0_245
.Lzsel_s2:
	v_mul_f32_e32 v100, 0xbfb8aa3b, v100
	v_mul_f32_e32 v96, 0xbfb8aa3b, v96
	v_mul_f32_e32 v101, 0xbfb8aa3b, v101
	v_mul_f32_e32 v97, 0xbfb8aa3b, v97
	v_mul_f32_e32 v102, 0xbfb8aa3b, v102
	v_mul_f32_e32 v98, 0xbfb8aa3b, v98
	v_mul_f32_e32 v103, 0xbfb8aa3b, v103
	v_mul_f32_e32 v99, 0xbfb8aa3b, v99
	v_exp_f32_e32 v100, v100
	v_exp_f32_e32 v96, v96
	v_exp_f32_e32 v101, v101
	v_exp_f32_e32 v97, v97
	v_exp_f32_e32 v102, v102
	v_exp_f32_e32 v98, v98
	v_exp_f32_e32 v103, v103
	v_exp_f32_e32 v99, v99
	v_add_f32_e32 v100, 1.0, v100
	v_add_f32_e32 v96, 1.0, v96
	v_add_f32_e32 v101, 1.0, v101
	v_add_f32_e32 v97, 1.0, v97
	v_add_f32_e32 v102, 1.0, v102
	v_add_f32_e32 v98, 1.0, v98
	v_add_f32_e32 v103, 1.0, v103
	v_add_f32_e32 v99, 1.0, v99
	v_rcp_f32_e32 v100, v100
	v_rcp_f32_e32 v96, v96
	v_rcp_f32_e32 v101, v101
	v_rcp_f32_e32 v97, v97
	v_rcp_f32_e32 v102, v102
	v_rcp_f32_e32 v98, v98
	v_rcp_f32_e32 v103, v103
	v_rcp_f32_e32 v99, v99
.LBB0_245:
	s_and_b64 vcc, exec, s[6:7]
	v_cvt_pk_bf16_f32 v100, v100, v101
	v_cvt_pk_bf16_f32 v101, v102, v103
	v_cvt_pk_bf16_f32 v102, v96, v97
	v_cvt_pk_bf16_f32 v103, v98, v99
	s_cbranch_vccnz .Lzsel_p3
	global_store_dwordx4 v[112:113], v[100:103], off offset:256 nt
	s_branch .Lzsel_s3
.Lzsel_p3:
	global_store_dwordx4 v[112:113], v[100:103], off offset:256
	s_branch .LBB0_247
.Lzsel_s3:
	v_mul_f32_e32 v92, 0xbfb8aa3b, v92
	v_mul_f32_e32 v88, 0xbfb8aa3b, v88
	v_mul_f32_e32 v93, 0xbfb8aa3b, v93
	v_mul_f32_e32 v89, 0xbfb8aa3b, v89
	v_mul_f32_e32 v94, 0xbfb8aa3b, v94
	v_mul_f32_e32 v90, 0xbfb8aa3b, v90
	v_mul_f32_e32 v95, 0xbfb8aa3b, v95
	v_mul_f32_e32 v91, 0xbfb8aa3b, v91
	v_exp_f32_e32 v92, v92
	v_exp_f32_e32 v88, v88
	v_exp_f32_e32 v93, v93
	v_exp_f32_e32 v89, v89
	v_exp_f32_e32 v94, v94
	v_exp_f32_e32 v90, v90
	v_exp_f32_e32 v95, v95
	v_exp_f32_e32 v91, v91
	v_add_f32_e32 v92, 1.0, v92
	v_add_f32_e32 v88, 1.0, v88
	v_add_f32_e32 v93, 1.0, v93
	v_add_f32_e32 v89, 1.0, v89
	v_add_f32_e32 v94, 1.0, v94
	v_add_f32_e32 v90, 1.0, v90
	v_add_f32_e32 v95, 1.0, v95
	v_add_f32_e32 v91, 1.0, v91
	v_rcp_f32_e32 v92, v92
	v_rcp_f32_e32 v88, v88
	v_rcp_f32_e32 v93, v93
	v_rcp_f32_e32 v89, v89
	v_rcp_f32_e32 v94, v94
	v_rcp_f32_e32 v90, v90
	v_rcp_f32_e32 v95, v95
	v_rcp_f32_e32 v91, v91
; __device__ __forceinline__ unsigned pk2(float lo, float hi) { unsigned r; asm("v_cvt_pk_bf16_f32 %0, %1, %2" : "=v"(r) : "v"(lo), "v"(hi)); return r; }
; __device__ __forceinline__ float sigmoidf_(float x) { return __builtin_amdgcn_rcpf(1.0f + __expf(-x)); }
;     __device__ __forceinline__ void operator()(const f32x4 (&acc)[2][2][4][2], const Unit& u, int wr, int wc, int fr, int fq) const {
;     ...
;             for (int m = 0; m < 4; ++m) { bf16_t* rowp = O + (size_t)(row0 + ai * HALF + m * 16) * ldc + col0;
; #pragma unroll
;                 for (int bj = 0; bj < 2; ++bj) { f32x4 v0 = acc[ai][bj][m][0], v1 = acc[ai][bj][m][1];
;                     if (sg) {
; #pragma unroll
;                         for (int j = 0; j < 4; ++j) { v0[j] = sigmoidf_(v0[j]); v1[j] = sigmoidf_(v1[j]); } }
;                     u32x4 w; w.x = pk2(v0[0], v0[1]); w.y = pk2(v0[2], v0[3]); w.z = pk2(v1[0], v1[1]); w.w = pk2(v1[2], v1[3]);
;                     *(u32x4*)(rowp + bj * HALF) = w; } }
.LBB0_247:
	v_or_b32_e32 v98, 32, v152
	v_mov_b64_e32 v[96:97], s[40:41]
	v_mad_i64_i32 v[96:97], s[0:1], v98, s75, v[96:97]
	v_lshl_add_u64 v[96:97], v[142:143], 1, v[96:97]
	s_and_b64 vcc, exec, s[6:7]
	v_cvt_pk_bf16_f32 v92, v92, v93
	v_cvt_pk_bf16_f32 v93, v94, v95
	v_cvt_pk_bf16_f32 v94, v88, v89
	v_cvt_pk_bf16_f32 v95, v90, v91
	s_cbranch_vccnz .Lzsel_p4
	global_store_dwordx4 v[96:97], v[92:95], off nt
	s_branch .Lzsel_s4
.Lzsel_p4:
	global_store_dwordx4 v[96:97], v[92:95], off
	s_branch .LBB0_249
.Lzsel_s4:
	v_mul_f32_e32 v84, 0xbfb8aa3b, v84
	v_mul_f32_e32 v80, 0xbfb8aa3b, v80
	v_mul_f32_e32 v85, 0xbfb8aa3b, v85
	v_mul_f32_e32 v81, 0xbfb8aa3b, v81
	v_mul_f32_e32 v86, 0xbfb8aa3b, v86
	v_mul_f32_e32 v82, 0xbfb8aa3b, v82
	v_mul_f32_e32 v87, 0xbfb8aa3b, v87
	v_mul_f32_e32 v83, 0xbfb8aa3b, v83
	v_exp_f32_e32 v84, v84
	v_exp_f32_e32 v80, v80
	v_exp_f32_e32 v85, v85
	v_exp_f32_e32 v81, v81
	v_exp_f32_e32 v86, v86
	v_exp_f32_e32 v82, v82
	v_exp_f32_e32 v87, v87
	v_exp_f32_e32 v83, v83
	v_add_f32_e32 v84, 1.0, v84
	v_add_f32_e32 v80, 1.0, v80
	v_add_f32_e32 v85, 1.0, v85
	v_add_f32_e32 v81, 1.0, v81
	v_add_f32_e32 v86, 1.0, v86
	v_add_f32_e32 v82, 1.0, v82
	v_add_f32_e32 v87, 1.0, v87
	v_add_f32_e32 v83, 1.0, v83
	v_rcp_f32_e32 v84, v84
	v_rcp_f32_e32 v80, v80
	v_rcp_f32_e32 v85, v85
	v_rcp_f32_e32 v81, v81
	v_rcp_f32_e32 v86, v86
	v_rcp_f32_e32 v82, v82
	v_rcp_f32_e32 v87, v87
	v_rcp_f32_e32 v83, v83
.LBB0_249:
	s_and_b64 vcc, exec, s[6:7]
	v_cvt_pk_bf16_f32 v84, v84, v85
	v_cvt_pk_bf16_f32 v85, v86, v87
	v_cvt_pk_bf16_f32 v86, v80, v81
	v_cvt_pk_bf16_f32 v87, v82, v83
	s_cbranch_vccnz .Lzsel_p5
	global_store_dwordx4 v[96:97], v[84:87], off offset:256 nt
	s_branch .Lzsel_s5
.Lzsel_p5:
	global_store_dwordx4 v[96:97], v[84:87], off offset:256
	s_branch .LBB0_251
.Lzsel_s5:
	v_mul_f32_e32 v76, 0xbfb8aa3b, v76
	v_mul_f32_e32 v72, 0xbfb8aa3b, v72
	v_mul_f32_e32 v77, 0xbfb8aa3b, v77
	v_mul_f32_e32 v73, 0xbfb8aa3b, v73
	v_mul_f32_e32 v78, 0xbfb8aa3b, v78
	v_mul_f32_e32 v74, 0xbfb8aa3b, v74
	v_mul_f32_e32 v79, 0xbfb8aa3b, v79
	v_mul_f32_e32 v75, 0xbfb8aa3b, v75
	v_exp_f32_e32 v76, v76
	v_exp_f32_e32 v72, v72
	v_exp_f32_e32 v77, v77
	v_exp_f32_e32 v73, v73
	v_exp_f32_e32 v78, v78
	v_exp_f32_e32 v74, v74
	v_exp_f32_e32 v79, v79
	v_exp_f32_e32 v75, v75
	v_add_f32_e32 v76, 1.0, v76
	v_add_f32_e32 v72, 1.0, v72
	v_add_f32_e32 v77, 1.0, v77
	v_add_f32_e32 v73, 1.0, v73
	v_add_f32_e32 v78, 1.0, v78
	v_add_f32_e32 v74, 1.0, v74
	v_add_f32_e32 v79, 1.0, v79
	v_add_f32_e32 v75, 1.0, v75
	v_rcp_f32_e32 v76, v76
	v_rcp_f32_e32 v72, v72
	v_rcp_f32_e32 v77, v77
	v_rcp_f32_e32 v73, v73
	v_rcp_f32_e32 v78, v78
	v_rcp_f32_e32 v74, v74
	v_rcp_f32_e32 v79, v79
	v_rcp_f32_e32 v75, v75
.LBB0_251:
	v_or_b32_e32 v82, 48, v152
	v_mov_b64_e32 v[80:81], s[40:41]
	v_mad_i64_i32 v[80:81], s[0:1], v82, s75, v[80:81]
	v_lshl_add_u64 v[80:81], v[142:143], 1, v[80:81]
	s_and_b64 vcc, exec, s[6:7]
	v_cvt_pk_bf16_f32 v76, v76, v77
	v_cvt_pk_bf16_f32 v77, v78, v79
	v_cvt_pk_bf16_f32 v78, v72, v73
	v_cvt_pk_bf16_f32 v79, v74, v75
	s_cbranch_vccnz .Lzsel_p6
	global_store_dwordx4 v[80:81], v[76:79], off nt
	s_branch .Lzsel_s6
.Lzsel_p6:
	global_store_dwordx4 v[80:81], v[76:79], off
	s_branch .LBB0_253
.Lzsel_s6:
	v_mul_f32_e32 v68, 0xbfb8aa3b, v68
	v_mul_f32_e32 v64, 0xbfb8aa3b, v64
	v_mul_f32_e32 v69, 0xbfb8aa3b, v69
	v_mul_f32_e32 v65, 0xbfb8aa3b, v65
	v_mul_f32_e32 v70, 0xbfb8aa3b, v70
	v_mul_f32_e32 v66, 0xbfb8aa3b, v66
	v_mul_f32_e32 v71, 0xbfb8aa3b, v71
	v_mul_f32_e32 v67, 0xbfb8aa3b, v67
	v_exp_f32_e32 v68, v68
	v_exp_f32_e32 v64, v64
	v_exp_f32_e32 v69, v69
	v_exp_f32_e32 v65, v65
	v_exp_f32_e32 v70, v70
	v_exp_f32_e32 v66, v66
	v_exp_f32_e32 v71, v71
	v_exp_f32_e32 v67, v67
	v_add_f32_e32 v68, 1.0, v68
	v_add_f32_e32 v64, 1.0, v64
	v_add_f32_e32 v69, 1.0, v69
	v_add_f32_e32 v65, 1.0, v65
	v_add_f32_e32 v70, 1.0, v70
	v_add_f32_e32 v66, 1.0, v66
	v_add_f32_e32 v71, 1.0, v71
	v_add_f32_e32 v67, 1.0, v67
	v_rcp_f32_e32 v68, v68
	v_rcp_f32_e32 v64, v64
	v_rcp_f32_e32 v69, v69
	v_rcp_f32_e32 v65, v65
	v_rcp_f32_e32 v70, v70
	v_rcp_f32_e32 v66, v66
	v_rcp_f32_e32 v71, v71
	v_rcp_f32_e32 v67, v67
.LBB0_253:
	s_and_b64 vcc, exec, s[6:7]
	v_cvt_pk_bf16_f32 v68, v68, v69
	v_cvt_pk_bf16_f32 v69, v70, v71
	v_cvt_pk_bf16_f32 v70, v64, v65
	v_cvt_pk_bf16_f32 v71, v66, v67
	s_cbranch_vccnz .Lzsel_p7
	global_store_dwordx4 v[80:81], v[68:71], off offset:256 nt
	s_branch .Lzsel_s7
.Lzsel_p7:
	global_store_dwordx4 v[80:81], v[68:71], off offset:256
	s_branch .LBB0_255
.Lzsel_s7:
	v_mul_f32_e32 v60, 0xbfb8aa3b, v60
	v_mul_f32_e32 v56, 0xbfb8aa3b, v56
	v_mul_f32_e32 v61, 0xbfb8aa3b, v61
	v_mul_f32_e32 v57, 0xbfb8aa3b, v57
	v_mul_f32_e32 v62, 0xbfb8aa3b, v62
	v_mul_f32_e32 v58, 0xbfb8aa3b, v58
	v_mul_f32_e32 v63, 0xbfb8aa3b, v63
	v_mul_f32_e32 v59, 0xbfb8aa3b, v59
	v_exp_f32_e32 v60, v60
	v_exp_f32_e32 v56, v56
	v_exp_f32_e32 v61, v61
	v_exp_f32_e32 v57, v57
	v_exp_f32_e32 v62, v62
	v_exp_f32_e32 v58, v58
	v_exp_f32_e32 v63, v63
	v_exp_f32_e32 v59, v59
	v_add_f32_e32 v60, 1.0, v60
	v_add_f32_e32 v56, 1.0, v56
	v_add_f32_e32 v61, 1.0, v61
	v_add_f32_e32 v57, 1.0, v57
	v_add_f32_e32 v62, 1.0, v62
	v_add_f32_e32 v58, 1.0, v58
	v_add_f32_e32 v63, 1.0, v63
	v_add_f32_e32 v59, 1.0, v59
	v_rcp_f32_e32 v60, v60
	v_rcp_f32_e32 v56, v56
	v_rcp_f32_e32 v61, v61
	v_rcp_f32_e32 v57, v57
	v_rcp_f32_e32 v62, v62
	v_rcp_f32_e32 v58, v58
	v_rcp_f32_e32 v63, v63
	v_rcp_f32_e32 v59, v59
.LBB0_255:
	v_add_u32_e32 v66, 0x80, v152
	v_mov_b64_e32 v[64:65], s[40:41]
	v_mad_i64_i32 v[64:65], s[0:1], v66, s75, v[64:65]
	v_lshl_add_u64 v[64:65], v[142:143], 1, v[64:65]
	s_and_b64 vcc, exec, s[6:7]
	v_cvt_pk_bf16_f32 v60, v60, v61
	v_cvt_pk_bf16_f32 v61, v62, v63
	v_cvt_pk_bf16_f32 v62, v56, v57
	v_cvt_pk_bf16_f32 v63, v58, v59
	s_cbranch_vccnz .Lzsel_p8
	global_store_dwordx4 v[64:65], v[60:63], off nt
	s_branch .Lzsel_s8
; __device__ __forceinline__ unsigned pk2(float lo, float hi) { unsigned r; asm("v_cvt_pk_bf16_f32 %0, %1, %2" : "=v"(r) : "v"(lo), "v"(hi)); return r; }
; __device__ __forceinline__ float sigmoidf_(float x) { return __builtin_amdgcn_rcpf(1.0f + __expf(-x)); }
;     __device__ __forceinline__ void operator()(const f32x4 (&acc)[2][2][4][2], const Unit& u, int wr, int wc, int fr, int fq) const {
;     ...
;             for (int m = 0; m < 4; ++m) { bf16_t* rowp = O + (size_t)(row0 + ai * HALF + m * 16) * ldc + col0;
; #pragma unroll
;                 for (int bj = 0; bj < 2; ++bj) { f32x4 v0 = acc[ai][bj][m][0], v1 = acc[ai][bj][m][1];
;                     if (sg) {
; #pragma unroll
;                         for (int j = 0; j < 4; ++j) { v0[j] = sigmoidf_(v0[j]); v1[j] = sigmoidf_(v1[j]); } }
;                     u32x4 w; w.x = pk2(v0[0], v0[1]); w.y = pk2(v0[2], v0[3]); w.z = pk2(v1[0], v1[1]); w.w = pk2(v1[2], v1[3]);
;                     *(u32x4*)(rowp + bj * HALF) = w; } }
.Lzsel_p8:
	global_store_dwordx4 v[64:65], v[60:63], off
	s_branch .LBB0_257
.Lzsel_s8:
	v_mul_f32_e32 v52, 0xbfb8aa3b, v52
	v_mul_f32_e32 v48, 0xbfb8aa3b, v48
	v_mul_f32_e32 v53, 0xbfb8aa3b, v53
	v_mul_f32_e32 v49, 0xbfb8aa3b, v49
	v_mul_f32_e32 v54, 0xbfb8aa3b, v54
	v_mul_f32_e32 v50, 0xbfb8aa3b, v50
	v_mul_f32_e32 v55, 0xbfb8aa3b, v55
	v_mul_f32_e32 v51, 0xbfb8aa3b, v51
	v_exp_f32_e32 v52, v52
	v_exp_f32_e32 v48, v48
	v_exp_f32_e32 v53, v53
	v_exp_f32_e32 v49, v49
	v_exp_f32_e32 v54, v54
	v_exp_f32_e32 v50, v50
	v_exp_f32_e32 v55, v55
	v_exp_f32_e32 v51, v51
	v_add_f32_e32 v52, 1.0, v52
	v_add_f32_e32 v48, 1.0, v48
	v_add_f32_e32 v53, 1.0, v53
	v_add_f32_e32 v49, 1.0, v49
	v_add_f32_e32 v54, 1.0, v54
	v_add_f32_e32 v50, 1.0, v50
	v_add_f32_e32 v55, 1.0, v55
	v_add_f32_e32 v51, 1.0, v51
	v_rcp_f32_e32 v52, v52
	v_rcp_f32_e32 v48, v48
	v_rcp_f32_e32 v53, v53
	v_rcp_f32_e32 v49, v49
	v_rcp_f32_e32 v54, v54
	v_rcp_f32_e32 v50, v50
	v_rcp_f32_e32 v55, v55
	v_rcp_f32_e32 v51, v51
.LBB0_257:
	s_and_b64 vcc, exec, s[6:7]
	v_cvt_pk_bf16_f32 v52, v52, v53
	v_cvt_pk_bf16_f32 v53, v54, v55
	v_cvt_pk_bf16_f32 v54, v48, v49
	v_cvt_pk_bf16_f32 v55, v50, v51
	s_cbranch_vccnz .Lzsel_p9
	global_store_dwordx4 v[64:65], v[52:55], off offset:256 nt
	s_branch .Lzsel_s9
.Lzsel_p9:
	global_store_dwordx4 v[64:65], v[52:55], off offset:256
	s_branch .LBB0_259
.Lzsel_s9:
	v_mul_f32_e32 v44, 0xbfb8aa3b, v44
	v_mul_f32_e32 v40, 0xbfb8aa3b, v40
	v_mul_f32_e32 v45, 0xbfb8aa3b, v45
	v_mul_f32_e32 v41, 0xbfb8aa3b, v41
	v_mul_f32_e32 v46, 0xbfb8aa3b, v46
	v_mul_f32_e32 v42, 0xbfb8aa3b, v42
	v_mul_f32_e32 v47, 0xbfb8aa3b, v47
	v_mul_f32_e32 v43, 0xbfb8aa3b, v43
	v_exp_f32_e32 v44, v44
	v_exp_f32_e32 v40, v40
	v_exp_f32_e32 v45, v45
	v_exp_f32_e32 v41, v41
	v_exp_f32_e32 v46, v46
	v_exp_f32_e32 v42, v42
	v_exp_f32_e32 v47, v47
	v_exp_f32_e32 v43, v43
	v_add_f32_e32 v44, 1.0, v44
	v_add_f32_e32 v40, 1.0, v40
	v_add_f32_e32 v45, 1.0, v45
	v_add_f32_e32 v41, 1.0, v41
	v_add_f32_e32 v46, 1.0, v46
	v_add_f32_e32 v42, 1.0, v42
	v_add_f32_e32 v47, 1.0, v47
	v_add_f32_e32 v43, 1.0, v43
	v_rcp_f32_e32 v44, v44
	v_rcp_f32_e32 v40, v40
	v_rcp_f32_e32 v45, v45
	v_rcp_f32_e32 v41, v41
	v_rcp_f32_e32 v46, v46
	v_rcp_f32_e32 v42, v42
	v_rcp_f32_e32 v47, v47
	v_rcp_f32_e32 v43, v43
.LBB0_259:
	v_add_u32_e32 v50, 0x90, v152
	v_mov_b64_e32 v[48:49], s[40:41]
	v_mad_i64_i32 v[48:49], s[0:1], v50, s75, v[48:49]
	v_lshl_add_u64 v[48:49], v[142:143], 1, v[48:49]
	s_and_b64 vcc, exec, s[6:7]
	v_cvt_pk_bf16_f32 v44, v44, v45
	v_cvt_pk_bf16_f32 v45, v46, v47
	v_cvt_pk_bf16_f32 v46, v40, v41
	v_cvt_pk_bf16_f32 v47, v42, v43
	s_cbranch_vccnz .Lzsel_p10
	global_store_dwordx4 v[48:49], v[44:47], off nt
	s_branch .Lzsel_s10
.Lzsel_p10:
	global_store_dwordx4 v[48:49], v[44:47], off
	s_branch .LBB0_261
.Lzsel_s10:
	v_mul_f32_e32 v36, 0xbfb8aa3b, v36
	v_mul_f32_e32 v32, 0xbfb8aa3b, v32
	v_mul_f32_e32 v37, 0xbfb8aa3b, v37
	v_mul_f32_e32 v33, 0xbfb8aa3b, v33
	v_mul_f32_e32 v38, 0xbfb8aa3b, v38
	v_mul_f32_e32 v34, 0xbfb8aa3b, v34
	v_mul_f32_e32 v39, 0xbfb8aa3b, v39
	v_mul_f32_e32 v35, 0xbfb8aa3b, v35
	v_exp_f32_e32 v36, v36
	v_exp_f32_e32 v32, v32
	v_exp_f32_e32 v37, v37
	v_exp_f32_e32 v33, v33
	v_exp_f32_e32 v38, v38
	v_exp_f32_e32 v34, v34
	v_exp_f32_e32 v39, v39
	v_exp_f32_e32 v35, v35
	v_add_f32_e32 v36, 1.0, v36
	v_add_f32_e32 v32, 1.0, v32
	v_add_f32_e32 v37, 1.0, v37
	v_add_f32_e32 v33, 1.0, v33
	v_add_f32_e32 v38, 1.0, v38
	v_add_f32_e32 v34, 1.0, v34
	v_add_f32_e32 v39, 1.0, v39
	v_add_f32_e32 v35, 1.0, v35
	v_rcp_f32_e32 v36, v36
	v_rcp_f32_e32 v32, v32
	v_rcp_f32_e32 v37, v37
	v_rcp_f32_e32 v33, v33
	v_rcp_f32_e32 v38, v38
	v_rcp_f32_e32 v34, v34
	v_rcp_f32_e32 v39, v39
	v_rcp_f32_e32 v35, v35
.LBB0_261:
	s_and_b64 vcc, exec, s[6:7]
	v_cvt_pk_bf16_f32 v36, v36, v37
	v_cvt_pk_bf16_f32 v37, v38, v39
	v_cvt_pk_bf16_f32 v38, v32, v33
	v_cvt_pk_bf16_f32 v39, v34, v35
	s_cbranch_vccnz .Lzsel_p11
	global_store_dwordx4 v[48:49], v[36:39], off offset:256 nt
	s_branch .Lzsel_s11
.Lzsel_p11:
	global_store_dwordx4 v[48:49], v[36:39], off offset:256
	s_branch .LBB0_263
.Lzsel_s11:
	v_mul_f32_e32 v28, 0xbfb8aa3b, v28
	v_mul_f32_e32 v24, 0xbfb8aa3b, v24
	v_mul_f32_e32 v29, 0xbfb8aa3b, v29
	v_mul_f32_e32 v25, 0xbfb8aa3b, v25
	v_mul_f32_e32 v30, 0xbfb8aa3b, v30
	v_mul_f32_e32 v26, 0xbfb8aa3b, v26
	v_mul_f32_e32 v31, 0xbfb8aa3b, v31
	v_mul_f32_e32 v27, 0xbfb8aa3b, v27
	v_exp_f32_e32 v28, v28
	v_exp_f32_e32 v24, v24
	v_exp_f32_e32 v29, v29
	v_exp_f32_e32 v25, v25
	v_exp_f32_e32 v30, v30
	v_exp_f32_e32 v26, v26
	v_exp_f32_e32 v31, v31
	v_exp_f32_e32 v27, v27
	v_add_f32_e32 v28, 1.0, v28
	v_add_f32_e32 v24, 1.0, v24
	v_add_f32_e32 v29, 1.0, v29
	v_add_f32_e32 v25, 1.0, v25
	v_add_f32_e32 v30, 1.0, v30
	v_add_f32_e32 v26, 1.0, v26
	v_add_f32_e32 v31, 1.0, v31
	v_add_f32_e32 v27, 1.0, v27
	v_rcp_f32_e32 v28, v28
	v_rcp_f32_e32 v24, v24
	v_rcp_f32_e32 v29, v29
	v_rcp_f32_e32 v25, v25
	v_rcp_f32_e32 v30, v30
	v_rcp_f32_e32 v26, v26
	v_rcp_f32_e32 v31, v31
	v_rcp_f32_e32 v27, v27
; __device__ __forceinline__ unsigned pk2(float lo, float hi) { unsigned r; asm("v_cvt_pk_bf16_f32 %0, %1, %2" : "=v"(r) : "v"(lo), "v"(hi)); return r; }
; __device__ __forceinline__ float sigmoidf_(float x) { return __builtin_amdgcn_rcpf(1.0f + __expf(-x)); }
;     __device__ __forceinline__ void operator()(const f32x4 (&acc)[2][2][4][2], const Unit& u, int wr, int wc, int fr, int fq) const {
;     ...
;             for (int m = 0; m < 4; ++m) { bf16_t* rowp = O + (size_t)(row0 + ai * HALF + m * 16) * ldc + col0;
; #pragma unroll
;                 for (int bj = 0; bj < 2; ++bj) { f32x4 v0 = acc[ai][bj][m][0], v1 = acc[ai][bj][m][1];
;                     if (sg) {
; #pragma unroll
;                         for (int j = 0; j < 4; ++j) { v0[j] = sigmoidf_(v0[j]); v1[j] = sigmoidf_(v1[j]); } }
;                     u32x4 w; w.x = pk2(v0[0], v0[1]); w.y = pk2(v0[2], v0[3]); w.z = pk2(v1[0], v1[1]); w.w = pk2(v1[2], v1[3]);
;                     *(u32x4*)(rowp + bj * HALF) = w; } }
.LBB0_263:
	v_add_u32_e32 v34, 0xa0, v152
	v_mov_b64_e32 v[32:33], s[40:41]
	v_mad_i64_i32 v[32:33], s[0:1], v34, s75, v[32:33]
	v_lshl_add_u64 v[32:33], v[142:143], 1, v[32:33]
	s_and_b64 vcc, exec, s[6:7]
	v_cvt_pk_bf16_f32 v28, v28, v29
	v_cvt_pk_bf16_f32 v29, v30, v31
	v_cvt_pk_bf16_f32 v30, v24, v25
	v_cvt_pk_bf16_f32 v31, v26, v27
	s_cbranch_vccnz .Lzsel_p12
	global_store_dwordx4 v[32:33], v[28:31], off nt
	s_branch .Lzsel_s12
.Lzsel_p12:
	global_store_dwordx4 v[32:33], v[28:31], off
	s_branch .LBB0_265
.Lzsel_s12:
	v_mul_f32_e32 v20, 0xbfb8aa3b, v20
	v_mul_f32_e32 v16, 0xbfb8aa3b, v16
	v_mul_f32_e32 v21, 0xbfb8aa3b, v21
	v_mul_f32_e32 v17, 0xbfb8aa3b, v17
	v_mul_f32_e32 v22, 0xbfb8aa3b, v22
	v_mul_f32_e32 v18, 0xbfb8aa3b, v18
	v_mul_f32_e32 v23, 0xbfb8aa3b, v23
	v_mul_f32_e32 v19, 0xbfb8aa3b, v19
	v_exp_f32_e32 v20, v20
	v_exp_f32_e32 v16, v16
	v_exp_f32_e32 v21, v21
	v_exp_f32_e32 v17, v17
	v_exp_f32_e32 v22, v22
	v_exp_f32_e32 v18, v18
	v_exp_f32_e32 v23, v23
	v_exp_f32_e32 v19, v19
	v_add_f32_e32 v20, 1.0, v20
	v_add_f32_e32 v16, 1.0, v16
	v_add_f32_e32 v21, 1.0, v21
	v_add_f32_e32 v17, 1.0, v17
	v_add_f32_e32 v22, 1.0, v22
	v_add_f32_e32 v18, 1.0, v18
	v_add_f32_e32 v23, 1.0, v23
	v_add_f32_e32 v19, 1.0, v19
	v_rcp_f32_e32 v20, v20
	v_rcp_f32_e32 v16, v16
	v_rcp_f32_e32 v21, v21
	v_rcp_f32_e32 v17, v17
	v_rcp_f32_e32 v22, v22
	v_rcp_f32_e32 v18, v18
	v_rcp_f32_e32 v23, v23
	v_rcp_f32_e32 v19, v19
.LBB0_265:
	s_and_b64 vcc, exec, s[6:7]
	v_cvt_pk_bf16_f32 v20, v20, v21
	v_cvt_pk_bf16_f32 v21, v22, v23
	v_cvt_pk_bf16_f32 v22, v16, v17
	v_cvt_pk_bf16_f32 v23, v18, v19
	s_cbranch_vccnz .Lzsel_p13
	global_store_dwordx4 v[32:33], v[20:23], off offset:256 nt
	s_branch .Lzsel_s13
.Lzsel_p13:
	global_store_dwordx4 v[32:33], v[20:23], off offset:256
	s_branch .LBB0_267
.Lzsel_s13:
	v_mul_f32_e32 v12, 0xbfb8aa3b, v12
	v_mul_f32_e32 v8, 0xbfb8aa3b, v8
	v_mul_f32_e32 v13, 0xbfb8aa3b, v13
	v_mul_f32_e32 v9, 0xbfb8aa3b, v9
	v_mul_f32_e32 v14, 0xbfb8aa3b, v14
	v_mul_f32_e32 v10, 0xbfb8aa3b, v10
	v_mul_f32_e32 v15, 0xbfb8aa3b, v15
	v_mul_f32_e32 v11, 0xbfb8aa3b, v11
	v_exp_f32_e32 v12, v12
	v_exp_f32_e32 v8, v8
	v_exp_f32_e32 v13, v13
	v_exp_f32_e32 v9, v9
	v_exp_f32_e32 v14, v14
	v_exp_f32_e32 v10, v10
	v_exp_f32_e32 v15, v15
	v_exp_f32_e32 v11, v11
	v_add_f32_e32 v12, 1.0, v12
	v_add_f32_e32 v8, 1.0, v8
	v_add_f32_e32 v13, 1.0, v13
	v_add_f32_e32 v9, 1.0, v9
	v_add_f32_e32 v14, 1.0, v14
	v_add_f32_e32 v10, 1.0, v10
	v_add_f32_e32 v15, 1.0, v15
	v_add_f32_e32 v11, 1.0, v11
	v_rcp_f32_e32 v12, v12
	v_rcp_f32_e32 v8, v8
	v_rcp_f32_e32 v13, v13
	v_rcp_f32_e32 v9, v9
	v_rcp_f32_e32 v14, v14
	v_rcp_f32_e32 v10, v10
	v_rcp_f32_e32 v15, v15
	v_rcp_f32_e32 v11, v11
.LBB0_267:
	v_add_u32_e32 v18, 0xb0, v152
	v_mov_b64_e32 v[16:17], s[40:41]
	v_mad_i64_i32 v[16:17], s[0:1], v18, s75, v[16:17]
	v_lshl_add_u64 v[16:17], v[142:143], 1, v[16:17]
	s_and_b64 vcc, exec, s[6:7]
	v_cvt_pk_bf16_f32 v12, v12, v13
	v_cvt_pk_bf16_f32 v13, v14, v15
	v_cvt_pk_bf16_f32 v14, v8, v9
	v_cvt_pk_bf16_f32 v15, v10, v11
	s_cbranch_vccnz .Lzsel_p14
	global_store_dwordx4 v[16:17], v[12:15], off nt
	s_branch .Lzsel_s14
.Lzsel_p14:
	global_store_dwordx4 v[16:17], v[12:15], off
	s_branch .LBB0_232
.Lzsel_s14:
	v_mul_f32_e32 v4, 0xbfb8aa3b, v4
	v_mul_f32_e32 v0, 0xbfb8aa3b, v0
	v_mul_f32_e32 v5, 0xbfb8aa3b, v5
	v_mul_f32_e32 v1, 0xbfb8aa3b, v1
	v_mul_f32_e32 v6, 0xbfb8aa3b, v6
	v_mul_f32_e32 v2, 0xbfb8aa3b, v2
	v_mul_f32_e32 v7, 0xbfb8aa3b, v7
	v_mul_f32_e32 v3, 0xbfb8aa3b, v3
	v_exp_f32_e32 v4, v4
	v_exp_f32_e32 v0, v0
	v_exp_f32_e32 v5, v5
	v_exp_f32_e32 v1, v1
	v_exp_f32_e32 v6, v6
	v_exp_f32_e32 v2, v2
	v_exp_f32_e32 v7, v7
	v_exp_f32_e32 v3, v3
	v_add_f32_e32 v4, 1.0, v4
	v_add_f32_e32 v0, 1.0, v0
	v_add_f32_e32 v5, 1.0, v5
	v_add_f32_e32 v1, 1.0, v1
	v_add_f32_e32 v6, 1.0, v6
	v_add_f32_e32 v2, 1.0, v2
	v_add_f32_e32 v7, 1.0, v7
	v_add_f32_e32 v3, 1.0, v3
	v_rcp_f32_e32 v4, v4
	v_rcp_f32_e32 v0, v0
	v_rcp_f32_e32 v5, v5
	v_rcp_f32_e32 v1, v1
	v_rcp_f32_e32 v6, v6
	v_rcp_f32_e32 v2, v2
	v_rcp_f32_e32 v7, v7
	v_rcp_f32_e32 v3, v3
	s_branch .LBB0_232
